# v53 plus: P1 epilogue row-norm reductions use v_permlane16/32_swap instead of ds_bpermute round trips (bit-identical)
# speedup vs baseline: 1.0052x; 1.0033x over previous
;     __device__ __forceinline__ void operator()(const f32x4 (&acc)[2][2][4][2], const Unit& u, int wr, int wc, int fr, int fq) const {
;     ...
;                     if (nrmw) { float q = (v0[0] * v0[0] + v0[1] * v0[1]) + (v0[2] * v0[2] + v0[3] * v0[3]) + (v1[0] * v1[0] + v1[1] * v1[1]) + (v1[2] * v1[2] + v1[3] * v1[3]);
;                         q += __shfl_xor(q, 16); q += __shfl_xor(q, 32); mxn[bj] = fmaxf(mxn[bj], q); }
.LBB0_294:
	s_andn2_b64 vcc, exec, s[0:1]
	v_mov_b32_e32 v209, 0
	s_cbranch_vccnz .LBB0_296
	v_pk_mul_f32 v[184:185], v[190:191], v[190:191]
	v_pk_mul_f32 v[186:187], v[188:189], v[188:189]
	s_nop 0
	v_pk_mov_b32 v[204:205], v[186:187], v[184:185] op_sel:[1,0]
	v_mov_b32_e32 v187, v185
	v_pk_add_f32 v[184:185], v[204:205], v[186:187]
	v_pk_mul_f32 v[186:187], v[230:231], v[230:231]
	v_pk_mul_f32 v[204:205], v[232:233], v[232:233]
	v_mov_b32_e32 v252, v186
	v_mov_b32_e32 v253, v204
	v_mov_b32_e32 v204, v187
	v_pk_add_f32 v[186:187], v[252:253], v[204:205]
	v_add_f32_e32 v184, v184, v185
	v_add_f32_e32 v184, v184, v187
	v_add_f32_e32 v184, v186, v184
	v_mov_b32_e32 v185, v184
	s_nop 1
	v_permlane16_swap_b32_e32 v185, v184
	s_waitcnt lgkmcnt(0)
	v_add_f32_e32 v184, v184, v185
	v_mov_b32_e32 v185, v184
	s_nop 1
	v_permlane32_swap_b32_e32 v185, v184
	s_waitcnt lgkmcnt(0)
	v_add_f32_e32 v184, v184, v185
	v_max_f32_e32 v209, 0, v184

;     __device__ __forceinline__ void operator()(const f32x4 (&acc)[2][2][4][2], const Unit& u, int wr, int wc, int fr, int fq) const {
;     ...
;                     if (nrmw) { float q = (v0[0] * v0[0] + v0[1] * v0[1]) + (v0[2] * v0[2] + v0[3] * v0[3]) + (v1[0] * v1[0] + v1[1] * v1[1]) + (v1[2] * v1[2] + v1[3] * v1[3]);
;                         q += __shfl_xor(q, 16); q += __shfl_xor(q, 32); mxn[bj] = fmaxf(mxn[bj], q); }
.LBB0_300:
	s_andn2_b64 vcc, exec, s[0:1]
	v_mov_b32_e32 v220, 0
	s_cbranch_vccnz .LBB0_302
	v_pk_mul_f32 v[188:189], v[182:183], v[182:183]
	v_pk_mul_f32 v[190:191], v[180:181], v[180:181]
	s_nop 0
	v_pk_mov_b32 v[204:205], v[190:191], v[188:189] op_sel:[1,0]
	v_mov_b32_e32 v191, v189
	v_pk_add_f32 v[188:189], v[204:205], v[190:191]
	v_pk_mul_f32 v[190:191], v[178:179], v[178:179]
	v_pk_mul_f32 v[204:205], v[176:177], v[176:177]
	v_mov_b32_e32 v210, v190
	v_mov_b32_e32 v211, v204
	v_mov_b32_e32 v204, v191
	v_pk_add_f32 v[190:191], v[210:211], v[204:205]
	v_add_f32_e32 v188, v188, v189
	v_add_f32_e32 v188, v188, v191
	v_add_f32_e32 v188, v190, v188
	v_mov_b32_e32 v189, v188
	s_nop 1
	v_permlane16_swap_b32_e32 v189, v188
	s_waitcnt lgkmcnt(0)
	v_add_f32_e32 v188, v188, v189
	v_mov_b32_e32 v189, v188
	s_nop 1
	v_permlane32_swap_b32_e32 v189, v188
	s_waitcnt lgkmcnt(0)
	v_add_f32_e32 v188, v188, v189
	v_max_f32_e32 v220, 0, v188

;     __device__ __forceinline__ void operator()(const f32x4 (&acc)[2][2][4][2], const Unit& u, int wr, int wc, int fr, int fq) const {
;     ...
;                     if (nrmw) { float q = (v0[0] * v0[0] + v0[1] * v0[1]) + (v0[2] * v0[2] + v0[3] * v0[3]) + (v1[0] * v1[0] + v1[1] * v1[1]) + (v1[2] * v1[2] + v1[3] * v1[3]);
;                         q += __shfl_xor(q, 16); q += __shfl_xor(q, 32); mxn[bj] = fmaxf(mxn[bj], q); }
.LBB0_314:
	s_andn2_b64 vcc, exec, s[0:1]
	s_cbranch_vccnz .LBB0_316
	v_pk_mul_f32 v[168:169], v[174:175], v[174:175]
	v_pk_mul_f32 v[204:205], v[172:173], v[172:173]
	s_nop 0
	v_pk_mov_b32 v[222:223], v[204:205], v[168:169] op_sel:[1,0]
	v_mov_b32_e32 v205, v169
	v_pk_add_f32 v[168:169], v[222:223], v[204:205]
	v_pk_mul_f32 v[204:205], v[170:171], v[170:171]
	v_pk_mul_f32 v[222:223], v[218:219], v[218:219]
	v_mov_b32_e32 v224, v204
	v_mov_b32_e32 v225, v222
	v_mov_b32_e32 v222, v205
	v_pk_add_f32 v[204:205], v[224:225], v[222:223]
	v_add_f32_e32 v168, v168, v169
	v_add_f32_e32 v168, v168, v205
	v_add_f32_e32 v168, v204, v168
	v_mov_b32_e32 v169, v168
	s_nop 1
	v_permlane16_swap_b32_e32 v169, v168
	s_waitcnt lgkmcnt(0)
	v_add_f32_e32 v168, v168, v169
	v_mov_b32_e32 v169, v168
	s_nop 1
	v_permlane32_swap_b32_e32 v169, v168
	s_waitcnt lgkmcnt(0)
	v_add_f32_e32 v168, v168, v169
	v_max_f32_e32 v169, v209, v209
	v_max_f32_e32 v209, v169, v168

;     __device__ __forceinline__ void operator()(const f32x4 (&acc)[2][2][4][2], const Unit& u, int wr, int wc, int fr, int fq) const {
;     ...
;                     if (nrmw) { float q = (v0[0] * v0[0] + v0[1] * v0[1]) + (v0[2] * v0[2] + v0[3] * v0[3]) + (v1[0] * v1[0] + v1[1] * v1[1]) + (v1[2] * v1[2] + v1[3] * v1[3]);
;                         q += __shfl_xor(q, 16); q += __shfl_xor(q, 32); mxn[bj] = fmaxf(mxn[bj], q); }
.LBB0_320:
	s_andn2_b64 vcc, exec, s[0:1]
	s_cbranch_vccnz .LBB0_322
	v_pk_mul_f32 v[170:171], v[166:167], v[166:167]
	v_pk_mul_f32 v[172:173], v[164:165], v[164:165]
	s_nop 0
	v_pk_mov_b32 v[174:175], v[172:173], v[170:171] op_sel:[1,0]
	v_mov_b32_e32 v173, v171
	v_pk_add_f32 v[170:171], v[174:175], v[172:173]
	v_pk_mul_f32 v[172:173], v[162:163], v[162:163]
	v_pk_mul_f32 v[174:175], v[160:161], v[160:161]
	v_mov_b32_e32 v176, v172
	v_mov_b32_e32 v177, v174
	v_mov_b32_e32 v174, v173
	v_pk_add_f32 v[172:173], v[176:177], v[174:175]
	v_add_f32_e32 v170, v170, v171
	v_add_f32_e32 v170, v170, v173
	v_add_f32_e32 v170, v172, v170
	v_mov_b32_e32 v171, v170
	s_nop 1
	v_permlane16_swap_b32_e32 v171, v170
	s_waitcnt lgkmcnt(0)
	v_add_f32_e32 v170, v170, v171
	v_mov_b32_e32 v171, v170
	s_nop 1
	v_permlane32_swap_b32_e32 v171, v170
	s_waitcnt lgkmcnt(0)
	v_add_f32_e32 v170, v170, v171
	v_max_f32_e32 v171, v220, v220
	v_max_f32_e32 v220, v171, v170

;     __device__ __forceinline__ void operator()(const f32x4 (&acc)[2][2][4][2], const Unit& u, int wr, int wc, int fr, int fq) const {
;     ...
;                     if (nrmw) { float q = (v0[0] * v0[0] + v0[1] * v0[1]) + (v0[2] * v0[2] + v0[3] * v0[3]) + (v1[0] * v1[0] + v1[1] * v1[1]) + (v1[2] * v1[2] + v1[3] * v1[3]);
;                         q += __shfl_xor(q, 16); q += __shfl_xor(q, 32); mxn[bj] = fmaxf(mxn[bj], q); }
.LBB0_334:
	s_andn2_b64 vcc, exec, s[0:1]
	s_cbranch_vccnz .LBB0_336
	v_pk_mul_f32 v[148:149], v[158:159], v[158:159]
	v_pk_mul_f32 v[182:183], v[156:157], v[156:157]
	s_nop 0
	v_pk_mov_b32 v[186:187], v[182:183], v[148:149] op_sel:[1,0]
	v_mov_b32_e32 v183, v149
	v_pk_add_f32 v[148:149], v[186:187], v[182:183]
	v_pk_mul_f32 v[182:183], v[150:151], v[150:151]
	v_pk_mul_f32 v[186:187], v[180:181], v[180:181]
	v_mov_b32_e32 v188, v182
	v_mov_b32_e32 v189, v186
	v_mov_b32_e32 v186, v183
	v_pk_add_f32 v[182:183], v[188:189], v[186:187]
	v_add_f32_e32 v148, v148, v149
	v_add_f32_e32 v148, v148, v183
	v_add_f32_e32 v148, v182, v148
	v_mov_b32_e32 v149, v148
	s_nop 1
	v_permlane16_swap_b32_e32 v149, v148
	s_waitcnt lgkmcnt(0)
	v_add_f32_e32 v148, v148, v149
	v_mov_b32_e32 v149, v148
	s_nop 1
	v_permlane32_swap_b32_e32 v149, v148
	s_waitcnt lgkmcnt(0)
	v_add_f32_e32 v148, v148, v149
	v_max_f32_e32 v149, v209, v209
	v_max_f32_e32 v209, v149, v148

;     __device__ __forceinline__ void operator()(const f32x4 (&acc)[2][2][4][2], const Unit& u, int wr, int wc, int fr, int fq) const {
;     ...
;                     if (nrmw) { float q = (v0[0] * v0[0] + v0[1] * v0[1]) + (v0[2] * v0[2] + v0[3] * v0[3]) + (v1[0] * v1[0] + v1[1] * v1[1]) + (v1[2] * v1[2] + v1[3] * v1[3]);
;                         q += __shfl_xor(q, 16); q += __shfl_xor(q, 32); mxn[bj] = fmaxf(mxn[bj], q); }
.LBB0_340:
	s_andn2_b64 vcc, exec, s[0:1]
	s_cbranch_vccnz .LBB0_342
	v_pk_mul_f32 v[150:151], v[142:143], v[142:143]
	v_pk_mul_f32 v[156:157], v[140:141], v[140:141]
	s_nop 0
	v_pk_mov_b32 v[158:159], v[156:157], v[150:151] op_sel:[1,0]
	v_mov_b32_e32 v157, v151
	v_pk_add_f32 v[150:151], v[158:159], v[156:157]
	v_pk_mul_f32 v[156:157], v[138:139], v[138:139]
	v_pk_mul_f32 v[158:159], v[136:137], v[136:137]
	v_mov_b32_e32 v160, v156
	v_mov_b32_e32 v161, v158
	v_mov_b32_e32 v158, v157
	v_pk_add_f32 v[156:157], v[160:161], v[158:159]
	v_add_f32_e32 v150, v150, v151
	v_add_f32_e32 v150, v150, v157
	v_add_f32_e32 v150, v156, v150
	v_mov_b32_e32 v151, v150
	s_nop 1
	v_permlane16_swap_b32_e32 v151, v150
	s_waitcnt lgkmcnt(0)
	v_add_f32_e32 v150, v150, v151
	v_mov_b32_e32 v151, v150
	s_nop 1
	v_permlane32_swap_b32_e32 v151, v150
	s_waitcnt lgkmcnt(0)
	v_add_f32_e32 v150, v150, v151
	v_max_f32_e32 v151, v220, v220
	v_max_f32_e32 v220, v151, v150

;     __device__ __forceinline__ void operator()(const f32x4 (&acc)[2][2][4][2], const Unit& u, int wr, int wc, int fr, int fq) const {
;     ...
;                     if (nrmw) { float q = (v0[0] * v0[0] + v0[1] * v0[1]) + (v0[2] * v0[2] + v0[3] * v0[3]) + (v1[0] * v1[0] + v1[1] * v1[1]) + (v1[2] * v1[2] + v1[3] * v1[3]);
;                         q += __shfl_xor(q, 16); q += __shfl_xor(q, 32); mxn[bj] = fmaxf(mxn[bj], q); }
.LBB0_354:
	s_andn2_b64 vcc, exec, s[0:1]
	s_cbranch_vccnz .LBB0_356
	v_pk_mul_f32 v[112:113], v[118:119], v[118:119]
	v_pk_mul_f32 v[166:167], v[116:117], v[116:117]
	s_nop 0
	v_pk_mov_b32 v[168:169], v[166:167], v[112:113] op_sel:[1,0]
	v_mov_b32_e32 v167, v113
	v_pk_add_f32 v[112:113], v[168:169], v[166:167]
	v_pk_mul_f32 v[166:167], v[114:115], v[114:115]
	v_pk_mul_f32 v[168:169], v[164:165], v[164:165]
	v_mov_b32_e32 v170, v166
	v_mov_b32_e32 v171, v168
	v_mov_b32_e32 v168, v167
	v_pk_add_f32 v[166:167], v[170:171], v[168:169]
	v_add_f32_e32 v112, v112, v113
	v_add_f32_e32 v112, v112, v167
	v_add_f32_e32 v112, v166, v112
	v_mov_b32_e32 v113, v112
	s_nop 1
	v_permlane16_swap_b32_e32 v113, v112
	s_waitcnt lgkmcnt(0)
	v_add_f32_e32 v112, v112, v113
	v_mov_b32_e32 v113, v112
	s_nop 1
	v_permlane32_swap_b32_e32 v113, v112
	s_waitcnt lgkmcnt(0)
	v_add_f32_e32 v112, v112, v113
	v_max_f32_e32 v113, v209, v209
	v_max_f32_e32 v209, v113, v112

;     __device__ __forceinline__ void operator()(const f32x4 (&acc)[2][2][4][2], const Unit& u, int wr, int wc, int fr, int fq) const {
;     ...
;                     if (nrmw) { float q = (v0[0] * v0[0] + v0[1] * v0[1]) + (v0[2] * v0[2] + v0[3] * v0[3]) + (v1[0] * v1[0] + v1[1] * v1[1]) + (v1[2] * v1[2] + v1[3] * v1[3]);
;                         q += __shfl_xor(q, 16); q += __shfl_xor(q, 32); mxn[bj] = fmaxf(mxn[bj], q); }
.LBB0_360:
	s_andn2_b64 vcc, exec, s[0:1]
	s_cbranch_vccnz .LBB0_362
	v_pk_mul_f32 v[114:115], v[110:111], v[110:111]
	v_pk_mul_f32 v[116:117], v[108:109], v[108:109]
	s_nop 0
	v_pk_mov_b32 v[118:119], v[116:117], v[114:115] op_sel:[1,0]
	v_mov_b32_e32 v117, v115
	v_pk_add_f32 v[114:115], v[118:119], v[116:117]
	v_pk_mul_f32 v[116:117], v[106:107], v[106:107]
	v_pk_mul_f32 v[118:119], v[104:105], v[104:105]
	v_mov_b32_e32 v136, v116
	v_mov_b32_e32 v137, v118
	v_mov_b32_e32 v118, v117
	v_pk_add_f32 v[116:117], v[136:137], v[118:119]
	v_add_f32_e32 v114, v114, v115
	v_add_f32_e32 v114, v114, v117
	v_add_f32_e32 v114, v116, v114
	v_mov_b32_e32 v115, v114
	s_nop 1
	v_permlane16_swap_b32_e32 v115, v114
	s_waitcnt lgkmcnt(0)
	v_add_f32_e32 v114, v114, v115
	v_mov_b32_e32 v115, v114
	s_nop 1
	v_permlane32_swap_b32_e32 v115, v114
	s_waitcnt lgkmcnt(0)
	v_add_f32_e32 v114, v114, v115
	v_max_f32_e32 v115, v220, v220
	v_max_f32_e32 v220, v115, v114

;     __device__ __forceinline__ void operator()(const f32x4 (&acc)[2][2][4][2], const Unit& u, int wr, int wc, int fr, int fq) const {
;     ...
;                     if (nrmw) { float q = (v0[0] * v0[0] + v0[1] * v0[1]) + (v0[2] * v0[2] + v0[3] * v0[3]) + (v1[0] * v1[0] + v1[1] * v1[1]) + (v1[2] * v1[2] + v1[3] * v1[3]);
;                         q += __shfl_xor(q, 16); q += __shfl_xor(q, 32); mxn[bj] = fmaxf(mxn[bj], q); }
.LBB0_376:
	s_andn2_b64 vcc, exec, s[0:1]
	s_cbranch_vccnz .LBB0_378
	v_pk_mul_f32 v[72:73], v[82:83], v[82:83]
	v_pk_mul_f32 v[118:119], v[80:81], v[80:81]
	s_nop 0
	v_pk_mov_b32 v[136:137], v[118:119], v[72:73] op_sel:[1,0]
	v_mov_b32_e32 v119, v73
	v_pk_add_f32 v[72:73], v[136:137], v[118:119]
	v_pk_mul_f32 v[118:119], v[74:75], v[74:75]
	v_pk_mul_f32 v[136:137], v[116:117], v[116:117]
	v_mov_b32_e32 v138, v118
	v_mov_b32_e32 v139, v136
	v_mov_b32_e32 v136, v119
	v_pk_add_f32 v[118:119], v[138:139], v[136:137]
	v_add_f32_e32 v72, v72, v73
	v_add_f32_e32 v72, v72, v119
	v_add_f32_e32 v72, v118, v72
	v_mov_b32_e32 v73, v72
	s_nop 1
	v_permlane16_swap_b32_e32 v73, v72
	s_waitcnt lgkmcnt(0)
	v_add_f32_e32 v72, v72, v73
	v_mov_b32_e32 v73, v72
	s_nop 1
	v_permlane32_swap_b32_e32 v73, v72
	s_waitcnt lgkmcnt(0)
	v_add_f32_e32 v72, v72, v73
	v_max_f32_e32 v73, v209, v209
	v_max_f32_e32 v209, v73, v72

;     __device__ __forceinline__ void operator()(const f32x4 (&acc)[2][2][4][2], const Unit& u, int wr, int wc, int fr, int fq) const {
;     ...
;                     if (nrmw) { float q = (v0[0] * v0[0] + v0[1] * v0[1]) + (v0[2] * v0[2] + v0[3] * v0[3]) + (v1[0] * v1[0] + v1[1] * v1[1]) + (v1[2] * v1[2] + v1[3] * v1[3]);
;                         q += __shfl_xor(q, 16); q += __shfl_xor(q, 32); mxn[bj] = fmaxf(mxn[bj], q); }
.LBB0_382:
	s_andn2_b64 vcc, exec, s[0:1]
	s_cbranch_vccnz .LBB0_384
	v_pk_mul_f32 v[74:75], v[70:71], v[70:71]
	v_pk_mul_f32 v[80:81], v[68:69], v[68:69]
	s_nop 0
	v_pk_mov_b32 v[82:83], v[80:81], v[74:75] op_sel:[1,0]
	v_mov_b32_e32 v81, v75
	v_pk_add_f32 v[74:75], v[82:83], v[80:81]
	v_pk_mul_f32 v[80:81], v[66:67], v[66:67]
	v_pk_mul_f32 v[82:83], v[64:65], v[64:65]
	v_mov_b32_e32 v104, v80
	v_mov_b32_e32 v105, v82
	v_mov_b32_e32 v82, v81
	v_pk_add_f32 v[80:81], v[104:105], v[82:83]
	v_add_f32_e32 v74, v74, v75
	v_add_f32_e32 v74, v74, v81
	v_add_f32_e32 v74, v80, v74
	v_mov_b32_e32 v75, v74
	s_nop 1
	v_permlane16_swap_b32_e32 v75, v74
	s_waitcnt lgkmcnt(0)
	v_add_f32_e32 v74, v74, v75
	v_mov_b32_e32 v75, v74
	s_nop 1
	v_permlane32_swap_b32_e32 v75, v74
	s_waitcnt lgkmcnt(0)
	v_add_f32_e32 v74, v74, v75
	v_max_f32_e32 v75, v220, v220
	v_max_f32_e32 v220, v75, v74

;     __device__ __forceinline__ void operator()(const f32x4 (&acc)[2][2][4][2], const Unit& u, int wr, int wc, int fr, int fq) const {
;     ...
;                     if (nrmw) { float q = (v0[0] * v0[0] + v0[1] * v0[1]) + (v0[2] * v0[2] + v0[3] * v0[3]) + (v1[0] * v1[0] + v1[1] * v1[1]) + (v1[2] * v1[2] + v1[3] * v1[3]);
;                         q += __shfl_xor(q, 16); q += __shfl_xor(q, 32); mxn[bj] = fmaxf(mxn[bj], q); }
.LBB0_396:
	s_andn2_b64 vcc, exec, s[0:1]
	s_cbranch_vccnz .LBB0_398
	v_pk_mul_f32 v[40:41], v[46:47], v[46:47]
	v_pk_mul_f32 v[82:83], v[44:45], v[44:45]
	s_nop 0
	v_pk_mov_b32 v[104:105], v[82:83], v[40:41] op_sel:[1,0]
	v_mov_b32_e32 v83, v41
	v_pk_add_f32 v[40:41], v[104:105], v[82:83]
	v_pk_mul_f32 v[82:83], v[42:43], v[42:43]
	v_pk_mul_f32 v[104:105], v[80:81], v[80:81]
	v_mov_b32_e32 v106, v82
	v_mov_b32_e32 v107, v104
	v_mov_b32_e32 v104, v83
	v_pk_add_f32 v[82:83], v[106:107], v[104:105]
	v_add_f32_e32 v40, v40, v41
	v_add_f32_e32 v40, v40, v83
	v_add_f32_e32 v40, v82, v40
	v_mov_b32_e32 v41, v40
	s_nop 1
	v_permlane16_swap_b32_e32 v41, v40
	s_waitcnt lgkmcnt(0)
	v_add_f32_e32 v40, v40, v41
	v_mov_b32_e32 v41, v40
	s_nop 1
	v_permlane32_swap_b32_e32 v41, v40
	s_waitcnt lgkmcnt(0)
	v_add_f32_e32 v40, v40, v41
	v_max_f32_e32 v41, v209, v209
	v_max_f32_e32 v209, v41, v40

;     __device__ __forceinline__ void operator()(const f32x4 (&acc)[2][2][4][2], const Unit& u, int wr, int wc, int fr, int fq) const {
;     ...
;                     if (nrmw) { float q = (v0[0] * v0[0] + v0[1] * v0[1]) + (v0[2] * v0[2] + v0[3] * v0[3]) + (v1[0] * v1[0] + v1[1] * v1[1]) + (v1[2] * v1[2] + v1[3] * v1[3]);
;                         q += __shfl_xor(q, 16); q += __shfl_xor(q, 32); mxn[bj] = fmaxf(mxn[bj], q); }
.LBB0_402:
	s_andn2_b64 vcc, exec, s[0:1]
	s_cbranch_vccnz .LBB0_404
	v_pk_mul_f32 v[42:43], v[38:39], v[38:39]
	v_pk_mul_f32 v[44:45], v[36:37], v[36:37]
	s_nop 0
	v_pk_mov_b32 v[46:47], v[44:45], v[42:43] op_sel:[1,0]
	v_mov_b32_e32 v45, v43
	v_pk_add_f32 v[42:43], v[46:47], v[44:45]
	v_pk_mul_f32 v[44:45], v[34:35], v[34:35]
	v_pk_mul_f32 v[46:47], v[32:33], v[32:33]
	v_mov_b32_e32 v64, v44
	v_mov_b32_e32 v65, v46
	v_mov_b32_e32 v46, v45
	v_pk_add_f32 v[44:45], v[64:65], v[46:47]
	v_add_f32_e32 v42, v42, v43
	v_add_f32_e32 v42, v42, v45
	v_add_f32_e32 v42, v44, v42
	v_mov_b32_e32 v43, v42
	s_nop 1
	v_permlane16_swap_b32_e32 v43, v42
	s_waitcnt lgkmcnt(0)
	v_add_f32_e32 v42, v42, v43
	v_mov_b32_e32 v43, v42
	s_nop 1
	v_permlane32_swap_b32_e32 v43, v42
	s_waitcnt lgkmcnt(0)
	v_add_f32_e32 v42, v42, v43
	v_max_f32_e32 v43, v220, v220
	v_max_f32_e32 v220, v43, v42

;     __device__ __forceinline__ void operator()(const f32x4 (&acc)[2][2][4][2], const Unit& u, int wr, int wc, int fr, int fq) const {
;     ...
;                     if (nrmw) { float q = (v0[0] * v0[0] + v0[1] * v0[1]) + (v0[2] * v0[2] + v0[3] * v0[3]) + (v1[0] * v1[0] + v1[1] * v1[1]) + (v1[2] * v1[2] + v1[3] * v1[3]);
;                         q += __shfl_xor(q, 16); q += __shfl_xor(q, 32); mxn[bj] = fmaxf(mxn[bj], q); }
.LBB0_416:
	s_andn2_b64 vcc, exec, s[0:1]
	s_cbranch_vccnz .LBB0_418
	v_pk_mul_f32 v[24:25], v[30:31], v[30:31]
	v_pk_mul_f32 v[46:47], v[28:29], v[28:29]
	s_nop 0
	v_pk_mov_b32 v[64:65], v[46:47], v[24:25] op_sel:[1,0]
	v_mov_b32_e32 v47, v25
	v_pk_add_f32 v[24:25], v[64:65], v[46:47]
	v_pk_mul_f32 v[46:47], v[26:27], v[26:27]
	v_pk_mul_f32 v[64:65], v[44:45], v[44:45]
	v_mov_b32_e32 v66, v46
	v_mov_b32_e32 v67, v64
	v_mov_b32_e32 v64, v47
	v_pk_add_f32 v[46:47], v[66:67], v[64:65]
	v_add_f32_e32 v24, v24, v25
	v_add_f32_e32 v24, v24, v47
	v_add_f32_e32 v24, v46, v24
	v_mov_b32_e32 v25, v24
	s_nop 1
	v_permlane16_swap_b32_e32 v25, v24
	s_waitcnt lgkmcnt(0)
	v_add_f32_e32 v24, v24, v25
	v_mov_b32_e32 v25, v24
	s_nop 1
	v_permlane32_swap_b32_e32 v25, v24
	s_waitcnt lgkmcnt(0)
	v_add_f32_e32 v24, v24, v25
	v_max_f32_e32 v25, v209, v209
	v_max_f32_e32 v209, v25, v24

;     __device__ __forceinline__ void operator()(const f32x4 (&acc)[2][2][4][2], const Unit& u, int wr, int wc, int fr, int fq) const {
;     ...
;                     if (nrmw) { float q = (v0[0] * v0[0] + v0[1] * v0[1]) + (v0[2] * v0[2] + v0[3] * v0[3]) + (v1[0] * v1[0] + v1[1] * v1[1]) + (v1[2] * v1[2] + v1[3] * v1[3]);
;                         q += __shfl_xor(q, 16); q += __shfl_xor(q, 32); mxn[bj] = fmaxf(mxn[bj], q); }
.LBB0_422:
	s_andn2_b64 vcc, exec, s[0:1]
	s_cbranch_vccnz .LBB0_424
	v_pk_mul_f32 v[26:27], v[22:23], v[22:23]
	v_pk_mul_f32 v[28:29], v[20:21], v[20:21]
	s_nop 0
	v_pk_mov_b32 v[30:31], v[28:29], v[26:27] op_sel:[1,0]
	v_mov_b32_e32 v29, v27
	v_pk_add_f32 v[26:27], v[30:31], v[28:29]
	v_pk_mul_f32 v[28:29], v[18:19], v[18:19]
	v_pk_mul_f32 v[30:31], v[16:17], v[16:17]
	v_mov_b32_e32 v32, v28
	v_mov_b32_e32 v33, v30
	v_mov_b32_e32 v30, v29
	v_pk_add_f32 v[28:29], v[32:33], v[30:31]
	v_add_f32_e32 v26, v26, v27
	v_add_f32_e32 v26, v26, v29
	v_add_f32_e32 v26, v28, v26
	v_mov_b32_e32 v27, v26
	s_nop 1
	v_permlane16_swap_b32_e32 v27, v26
	s_waitcnt lgkmcnt(0)
	v_add_f32_e32 v26, v26, v27
	v_mov_b32_e32 v27, v26
	s_nop 1
	v_permlane32_swap_b32_e32 v27, v26
	s_waitcnt lgkmcnt(0)
	v_add_f32_e32 v26, v26, v27
	v_max_f32_e32 v27, v220, v220
	v_max_f32_e32 v220, v27, v26

;     __device__ __forceinline__ void operator()(const f32x4 (&acc)[2][2][4][2], const Unit& u, int wr, int wc, int fr, int fq) const {
;     ...
;                     if (nrmw) { float q = (v0[0] * v0[0] + v0[1] * v0[1]) + (v0[2] * v0[2] + v0[3] * v0[3]) + (v1[0] * v1[0] + v1[1] * v1[1]) + (v1[2] * v1[2] + v1[3] * v1[3]);
;                         q += __shfl_xor(q, 16); q += __shfl_xor(q, 32); mxn[bj] = fmaxf(mxn[bj], q); }
.LBB0_436:
	s_andn2_b64 vcc, exec, s[0:1]
	s_cbranch_vccnz .LBB0_438
	v_pk_mul_f32 v[8:9], v[14:15], v[14:15]
	v_pk_mul_f32 v[30:31], v[12:13], v[12:13]
	s_nop 0
	v_pk_mov_b32 v[32:33], v[30:31], v[8:9] op_sel:[1,0]
	v_mov_b32_e32 v31, v9
	v_pk_add_f32 v[8:9], v[32:33], v[30:31]
	v_pk_mul_f32 v[30:31], v[10:11], v[10:11]
	v_pk_mul_f32 v[32:33], v[28:29], v[28:29]
	v_mov_b32_e32 v34, v30
	v_mov_b32_e32 v35, v32
	v_mov_b32_e32 v32, v31
	v_pk_add_f32 v[30:31], v[34:35], v[32:33]
	v_add_f32_e32 v8, v8, v9
	v_add_f32_e32 v8, v8, v31
	v_add_f32_e32 v8, v30, v8
	v_mov_b32_e32 v9, v8
	s_nop 1
	v_permlane16_swap_b32_e32 v9, v8
	s_waitcnt lgkmcnt(0)
	v_add_f32_e32 v8, v8, v9
	v_mov_b32_e32 v9, v8
	s_nop 1
	v_permlane32_swap_b32_e32 v9, v8
	s_waitcnt lgkmcnt(0)
	v_add_f32_e32 v8, v8, v9
	v_max_f32_e32 v9, v209, v209
	v_max_f32_e32 v209, v9, v8

;     __device__ __forceinline__ void operator()(const f32x4 (&acc)[2][2][4][2], const Unit& u, int wr, int wc, int fr, int fq) const {
;     ...
;                     if (nrmw) { float q = (v0[0] * v0[0] + v0[1] * v0[1]) + (v0[2] * v0[2] + v0[3] * v0[3]) + (v1[0] * v1[0] + v1[1] * v1[1]) + (v1[2] * v1[2] + v1[3] * v1[3]);
;                         q += __shfl_xor(q, 16); q += __shfl_xor(q, 32); mxn[bj] = fmaxf(mxn[bj], q); }
.LBB0_442:
	s_andn2_b64 vcc, exec, s[0:1]
	s_cbranch_vccnz .LBB0_444
	v_pk_mul_f32 v[10:11], v[6:7], v[6:7]
	v_pk_mul_f32 v[12:13], v[4:5], v[4:5]
	s_nop 0
	v_pk_mov_b32 v[14:15], v[12:13], v[10:11] op_sel:[1,0]
	v_mov_b32_e32 v13, v11
	v_pk_add_f32 v[10:11], v[14:15], v[12:13]
	v_pk_mul_f32 v[12:13], v[2:3], v[2:3]
	v_pk_mul_f32 v[14:15], v[0:1], v[0:1]
	v_mov_b32_e32 v16, v12
	v_mov_b32_e32 v17, v14
	v_mov_b32_e32 v14, v13
	v_pk_add_f32 v[12:13], v[16:17], v[14:15]
	v_add_f32_e32 v10, v10, v11
	v_add_f32_e32 v10, v10, v13
	v_add_f32_e32 v10, v12, v10
	v_mov_b32_e32 v11, v10
	s_nop 1
	v_permlane16_swap_b32_e32 v11, v10
	s_waitcnt lgkmcnt(0)
	v_add_f32_e32 v10, v10, v11
	v_mov_b32_e32 v11, v10
	s_nop 1
	v_permlane32_swap_b32_e32 v11, v10
	s_waitcnt lgkmcnt(0)
	v_add_f32_e32 v10, v10, v11
	v_max_f32_e32 v11, v220, v220
	v_max_f32_e32 v220, v11, v10
